# v32 + P2 conv moved into P3 dynamic queue as interleaved work items (de-bursts HBM traffic under compute-bound attention)
# speedup vs baseline: 1.0102x; 1.0078x over previous
.LBB0_2:
	v_writelane_b32 v248, s86, 6
	s_load_dword s4, s[0:1], 0xa0
	v_lshrrev_b32_e32 v1, 9, v202
	v_lshl_add_u32 v2, v202, 2, 0
	v_xor_b32_e32 v1, 7, v1
	v_add_u32_e32 v2, 0x20000, v2
	v_mov_b32_e32 v3, 0
	s_waitcnt lgkmcnt(0)
	v_writelane_b32 v249, s4, 0
	ds_write2st64_b32 v2, v3, v3 offset1:8
	ds_write2st64_b32 v2, v3, v3 offset0:16 offset1:24
	v_or_b32_e32 v2, 0x800, v202
	v_cmp_lt_u32_e32 vcc, 4, v1
	v_cmp_lt_u32_e64 s[4:5], 3, v1
	s_and_saveexec_b64 s[6:7], s[4:5]
	v_lshl_add_u32 v4, v2, 2, 0
	v_add_u32_e32 v4, 0x20000, v4
	ds_write_b32 v4, v3
	s_or_b64 exec, exec, s[6:7]
	s_and_saveexec_b64 s[4:5], vcc
	s_add_i32 s6, 0, 0x20000
	v_lshl_add_u32 v2, v2, 2, s6
	v_mov_b32_e32 v3, 0
	ds_write_b32 v2, v3 offset:2048
	s_or_b64 exec, exec, s[4:5]
	v_or_b32_e32 v2, 0xc00, v202
	v_cmp_lt_u32_e32 vcc, 6, v1
	v_cmp_lt_u32_e64 s[4:5], 5, v1
	s_and_saveexec_b64 s[6:7], s[4:5]
	v_lshl_add_u32 v1, v2, 2, 0
	v_add_u32_e32 v1, 0x20000, v1
	v_mov_b32_e32 v3, 0
	ds_write_b32 v1, v3
	s_or_b64 exec, exec, s[6:7]
	s_load_dwordx4 s[4:7], s[0:1], 0x80
	s_waitcnt lgkmcnt(0)
	v_writelane_b32 v249, s4, 1
	s_nop 1
	v_writelane_b32 v249, s5, 2
	v_writelane_b32 v249, s6, 3
	v_writelane_b32 v249, s7, 4
	s_and_saveexec_b64 s[4:5], vcc
	s_add_i32 s6, 0, 0x20000
	v_lshl_add_u32 v1, v2, 2, s6
	v_mov_b32_e32 v2, 0
	ds_write_b32 v1, v2 offset:2048
	s_or_b64 exec, exec, s[4:5]
	s_load_dword s8, s[0:1], 0x90
	s_load_dwordx4 s[4:7], s[0:1], 0x80
	s_waitcnt lgkmcnt(0)
	s_barrier
	s_getreg_b32 s4, hwreg(HW_REG_XCC_ID, 0, 4)
	s_add_u32 s80, s6, 0x100000
	s_addc_u32 s81, s7, 0
	s_and_b32 s83, s4, 15
	v_cmp_eq_u32_e64 s[88:89], 0, v202
	s_and_saveexec_b64 s[4:5], s[88:89]
	s_cbranch_execz .LBB0_13
	s_mov_b64 s[6:7], exec
	v_mbcnt_lo_u32_b32 v1, s6, 0
	v_mbcnt_hi_u32_b32 v1, s7, v1
	v_cmp_eq_u32_e32 vcc, 0, v1
	s_and_b64 s[10:11], exec, vcc
	s_mov_b64 exec, s[10:11]
	s_cbranch_execz .LBB0_13
	s_lshl_b32 s9, s83, 8
	s_bcnt1_i32_b64 s6, s[6:7]
	v_mov_b32_e32 v1, s9
	v_mov_b32_e32 v2, s6
	global_atomic_add v1, v2, s[80:81] offset:1024

.LBB0_413:
	v_writelane_b32 v249, s88, 37
	s_nop 1
	v_writelane_b32 v249, s89, 38
	s_or_b64 exec, exec, s[0:1]
	v_readlane_b32 s0, v249, 1
	v_readlane_b32 s2, v249, 3
	v_readlane_b32 s3, v249, 4
	s_add_u32 s68, s2, 0x14000000
	s_addc_u32 s69, s3, 0
	s_cmpk_lt_i32 s52, 0x800
	v_lshlrev_b32_e32 v62, 2, v202
	v_readlane_b32 s1, v249, 2
	s_waitcnt lgkmcnt(0)
	s_barrier
	s_cbranch_scc0 .LBB0_441
	v_writelane_b32 v248, s6, 12
	v_writelane_b32 v248, s7, 13
	v_and_b32_e32 v0, 56, v160
	v_and_b32_e32 v1, 64, v62
	v_readlane_b32 s8, v249, 5
	v_add_lshl_u32 v4, v1, v0, 2
	v_readlane_b32 s16, v249, 13
	v_readlane_b32 s17, v249, 14
	s_nop 4
	global_load_dwordx4 v[0:3], v4, s[16:17] offset:272
	s_nop 0
	global_load_dwordx4 v[4:7], v4, s[16:17] offset:256
	v_and_b32_e32 v8, 16, v202
	v_mov_b32_e32 v9, 0x200
	v_mov_b32_e32 v10, 0x100
	v_cmp_eq_u32_e32 vcc, 0, v8
	s_movk_i32 s0, 0x78
	v_readlane_b32 s2, v249, 33
	v_cndmask_b32_e32 v8, v9, v10, vcc
	v_and_or_b32 v8, v160, s0, v8
	v_lshlrev_b32_e32 v8, 1, v8
	v_mov_b32_e32 v9, 0
	v_readlane_b32 s3, v249, 34
	v_readlane_b32 s9, v249, 6
	v_readlane_b32 s10, v249, 7
	v_lshl_add_u64 v[44:45], s[2:3], 0, v[8:9]
	v_mbcnt_hi_u32_b32 v8, -1, v194
	v_and_b32_e32 v11, 64, v8
	v_xor_b32_e32 v10, 1, v8
	v_add_u32_e32 v11, 64, v11
	v_cmp_lt_i32_e32 vcc, v10, v11
	s_add_u32 s2, s6, 0x1000
	s_addc_u32 s3, s7, 0
	v_cndmask_b32_e32 v10, v8, v10, vcc
	v_lshlrev_b32_e32 v60, 2, v10
	v_xor_b32_e32 v10, 2, v8
	v_cmp_lt_i32_e32 vcc, v10, v11
	v_readlane_b32 s11, v249, 8
	s_add_u32 s8, s6, 0x2000
	v_cndmask_b32_e32 v10, v8, v10, vcc
	v_lshlrev_b32_e32 v61, 2, v10
	v_xor_b32_e32 v10, 4, v8
	v_cmp_lt_i32_e32 vcc, v10, v11
	v_readlane_b32 s20, v249, 17
	v_readlane_b32 s21, v249, 18
	v_cndmask_b32_e32 v8, v8, v10, vcc
	s_addc_u32 s9, s7, 0
	s_lshl_b32 s10, s82, 7
	s_lshl_b32 s11, s50, 4
	v_cmp_gt_u32_e64 s[0:1], 32, v159
	v_lshlrev_b32_e32 v63, 2, v8
	s_add_i32 s20, s10, s11
	s_lshl_b32 s21, s86, 7
	v_mov_b32_e32 v64, 0x358637bd
	v_mov_b32_e32 v65, 0x600
	v_mov_b32_e32 v66, 0xc00
	v_readlane_b32 s12, v249, 9
	v_readlane_b32 s13, v249, 10
	v_readlane_b32 s14, v249, 11
	v_readlane_b32 s15, v249, 12
	v_readlane_b32 s18, v249, 15
	v_readlane_b32 s19, v249, 16
	v_readlane_b32 s22, v249, 19
	v_readlane_b32 s23, v249, 20

.LBB0_433:
	v_readlane_b32 s10, v248, 6
	s_nop 1
	s_cmp_eq_u32 s10, 0x100
	s_cbranch_scc1 .Lp2_noconv
	s_lshl_b32 s12, s52, 4
	s_and_b32 s10, s52, 0xff
	s_cmp_lg_u32 s10, 0
	s_cselect_b64 s[10:11], -1, 0
	s_ashr_i32 s13, s12, 31
	s_lshl_b64 s[12:13], s[12:13], 11
	s_add_u32 s14, s74, s12
	s_addc_u32 s15, s75, s13
	s_add_u32 s12, s14, 0xfffff800
	s_addc_u32 s13, s15, -1
	s_add_u32 s14, s14, 0xfffff000
	s_mov_b32 s22, 0
	s_addc_u32 s15, s15, -1
	s_mov_b64 s[18:19], -1

.Lp2_noconv:
	s_add_i32 s52, s52, s51
	s_add_i32 s20, s20, s21
	s_cmpk_gt_i32 s52, 0x7ff
	s_cbranch_scc0 .LBB0_415

.LBB0_502:
	s_or_b64 exec, exec, s[0:1]
	v_readlane_b32 s0, v249, 51
	s_waitcnt lgkmcnt(0)
	s_barrier
	v_mov_b32_e32 v0, s0
	ds_read_b32 v0, v0
	s_movk_i32 s0, 0x400
	s_cmp_eq_u32 s88, 0x100
	s_cselect_b32 s0, 0x500, s0
	s_waitcnt lgkmcnt(0)
	s_barrier
	v_cmp_gt_i32_e32 vcc, s0, v0
	v_readfirstlane_b32 s6, v0
	s_cbranch_vccz .LBB0_746

.LBB0_507:
	s_or_b64 exec, exec, s[0:1]
	s_cmp_lg_u32 s88, 0x100
	s_cbranch_scc1 .Lp3_attn
	s_mul_hi_u32 s0, s6, 0xcccccccd
	s_lshr_b32 s0, s0, 2
	s_mul_i32 s1, s0, 5
	s_sub_i32 s1, s6, s1
	s_cmp_eq_u32 s1, 4
	s_cbranch_scc1 .Lp3_conv
	s_lshl_b32 s0, s0, 2
	s_add_i32 s6, s0, s1
.Lp3_attn:
	s_cmpk_gt_i32 s6, 0x16f
	s_mov_b64 s[0:1], -1
	s_cbranch_scc0 .LBB0_516
	s_cmpk_gt_u32 s6, 0x2ef
	s_cbranch_scc0 .LBB0_510
	s_add_i32 s0, s6, 0xfffffd10
	s_lshr_b32 s0, s0, 4
	s_sub_i32 s79, 16, s0
	s_bfe_u32 s13, s6, 0x10003
	s_and_b32 s12, s6, 7
	s_mov_b64 s[0:1], 0

.Lp3_item_end:
	s_and_saveexec_b64 s[0:1], s[96:97]
	s_cbranch_execz .LBB0_502
	v_readlane_b32 s2, v249, 51
	s_nop 1
	v_mov_b32_e32 v0, s2
	ds_write_b32 v0, v164
	s_branch .LBB0_502
.Lp3_conv:
	v_readfirstlane_b32 s1, v202
	v_mov_b32_e32 v200, v164
	s_lshr_b32 s1, s1, 6
	s_lshl_b32 s52, s0, 3
	s_add_i32 s52, s52, s1
	s_lshl_b32 s20, s52, 4
	v_readlane_b32 s36, v248, 12
	v_readlane_b32 s37, v248, 13
	v_readlane_b32 s4, v249, 3
	v_readlane_b32 s5, v249, 4
	s_nop 1
	s_add_u32 s2, s36, 0x1000
	s_addc_u32 s3, s37, 0
	s_add_u32 s8, s36, 0x2000
	s_addc_u32 s9, s37, 0
	s_add_u32 s4, s4, 0x10000000
	s_addc_u32 s5, s5, 0
	v_and_b32_e32 v128, 63, v202
	v_lshlrev_b32_e32 v128, 3, v128
	v_mov_b32_e32 v9, 0
	v_mov_b32_e32 v66, 0xc00
	s_lshl_b32 s12, s52, 4
	s_and_b32 s10, s52, 0xff
	s_cmp_lg_u32 s10, 0
	s_cselect_b64 s[10:11], -1, 0
	s_ashr_i32 s13, s12, 31
	s_lshl_b64 s[12:13], s[12:13], 11
	s_add_u32 s14, s74, s12
	s_addc_u32 s15, s75, s13
	s_add_u32 s12, s14, 0xfffff800
	s_addc_u32 s13, s15, -1
	s_add_u32 s14, s14, 0xfffff000
	s_mov_b32 s22, 0
	s_addc_u32 s15, s15, -1
	s_mov_b64 s[18:19], -1
.Lcq_434:
	v_or_b32_e32 v8, s22, v128
	v_lshlrev_b64 v[10:11], 2, v[8:9]
	v_lshl_add_u64 v[16:17], s[36:37], 0, v[10:11]
	v_lshl_add_u64 v[24:25], s[2:3], 0, v[10:11]
	v_lshl_add_u64 v[10:11], s[8:9], 0, v[10:11]
	global_load_dwordx4 v[12:15], v[16:17], off offset:16
	s_waitcnt lgkmcnt(0)
	global_load_dwordx4 v[16:19], v[16:17], off
	s_nop 0
	global_load_dwordx4 v[20:23], v[24:25], off offset:16
	s_nop 0
	global_load_dwordx4 v[24:27], v[24:25], off
	s_nop 0
	global_load_dwordx4 v[28:31], v[10:11], off offset:16
	global_load_dwordx4 v[32:35], v[10:11], off
	s_andn2_b64 vcc, exec, s[10:11]
	v_lshlrev_b64 v[48:49], 1, v[8:9]
	s_cbranch_vccnz .Lcq_436
	v_lshl_add_u64 v[10:11], s[12:13], 0, v[48:49]
	v_lshl_add_u64 v[40:41], s[14:15], 0, v[48:49]
	global_load_dwordx4 v[36:39], v[10:11], off
	s_nop 0
	global_load_dwordx4 v[40:43], v[40:41], off
	s_branch .Lcq_437

.Lcq_438:
	s_add_i32 s19, s20, s18
	s_add_i32 s22, s19, 4
	s_add_i32 s26, s19, 5
	s_add_i32 s28, s19, 6
	s_add_i32 s30, s19, 7
	s_waitcnt vmcnt(1)
	v_lshlrev_b32_e32 v52, 16, v37
	v_and_b32_e32 v53, 0xffff0000, v37
	v_lshlrev_b32_e32 v54, 16, v38
	v_and_b32_e32 v55, 0xffff0000, v38
	v_lshlrev_b32_e32 v56, 16, v39
	v_and_b32_e32 v57, 0xffff0000, v39
	s_ashr_i32 s23, s22, 31
	s_ashr_i32 s27, s26, 31
	s_ashr_i32 s29, s28, 31
	s_ashr_i32 s31, s30, 31
	s_waitcnt vmcnt(0)
	v_lshlrev_b32_e32 v58, 16, v40
	v_and_b32_e32 v59, 0xffff0000, v40
	v_lshlrev_b32_e32 v50, 16, v36
	v_and_b32_e32 v51, 0xffff0000, v36
	v_lshlrev_b32_e32 v40, 16, v41
	v_and_b32_e32 v41, 0xffff0000, v41
	v_lshlrev_b32_e32 v36, 16, v42
	v_and_b32_e32 v37, 0xffff0000, v42
	v_lshlrev_b32_e32 v42, 16, v43
	v_and_b32_e32 v43, 0xffff0000, v43
	v_pk_mul_f32 v[68:69], v[26:27], v[52:53]
	v_pk_mul_f32 v[70:71], v[20:21], v[54:55]
	v_pk_mul_f32 v[72:73], v[22:23], v[56:57]
	v_mad_i64_i32 v[98:99], s[38:39], s22, v66, v[48:49]
	v_mad_i64_i32 v[100:101], s[38:39], s26, v66, v[48:49]
	v_mad_i64_i32 v[102:103], s[38:39], s28, v66, v[48:49]
	v_mad_i64_i32 v[104:105], s[38:39], s30, v66, v[48:49]
	s_lshl_b64 s[22:23], s[22:23], 11
	s_lshl_b64 s[26:27], s[26:27], 11
	s_lshl_b64 s[28:29], s[28:29], 11
	s_lshl_b64 s[30:31], s[30:31], 11
	v_pk_mul_f32 v[38:39], v[24:25], v[50:51]
	v_pk_fma_f32 v[92:93], v[18:19], v[40:41], v[68:69]
	v_pk_fma_f32 v[94:95], v[12:13], v[36:37], v[70:71]
	v_pk_fma_f32 v[96:97], v[14:15], v[42:43], v[72:73]
	v_lshl_add_u64 v[40:41], v[10:11], 0, s[22:23]
	v_lshl_add_u64 v[36:37], v[46:47], 0, s[22:23]
	v_lshl_add_u64 v[72:73], v[10:11], 0, s[26:27]
	v_lshl_add_u64 v[68:69], v[46:47], 0, s[26:27]
	v_lshl_add_u64 v[80:81], v[10:11], 0, s[28:29]
	v_lshl_add_u64 v[76:77], v[46:47], 0, s[28:29]
	v_lshl_add_u64 v[88:89], v[10:11], 0, s[30:31]
	v_lshl_add_u64 v[84:85], v[46:47], 0, s[30:31]
	v_pk_fma_f32 v[58:59], v[16:17], v[58:59], v[38:39]
	global_load_dwordx4 v[36:39], v[36:37], off
	s_nop 0
	global_load_dwordx4 v[40:43], v[40:41], off
	s_nop 0
	global_load_dwordx4 v[68:71], v[68:69], off
	s_nop 0
	global_load_dwordx4 v[72:75], v[72:73], off
	s_nop 0
	global_load_dwordx4 v[76:79], v[76:77], off
	s_nop 0
	global_load_dwordx4 v[80:83], v[80:81], off
	s_nop 0
	global_load_dwordx4 v[84:87], v[84:85], off
	s_nop 0
	global_load_dwordx4 v[88:91], v[88:89], off
	s_add_i32 s18, s18, 4
	s_cmp_gt_u32 s18, 11
	s_waitcnt vmcnt(7)
	v_lshlrev_b32_e32 v106, 16, v36
	v_and_b32_e32 v107, 0xffff0000, v36
	s_waitcnt vmcnt(6)
	v_lshlrev_b32_e32 v108, 16, v40
	v_and_b32_e32 v109, 0xffff0000, v40
	v_lshlrev_b32_e32 v110, 16, v37
	v_and_b32_e32 v111, 0xffff0000, v37
	v_lshlrev_b32_e32 v112, 16, v41
	v_and_b32_e32 v113, 0xffff0000, v41
	v_lshlrev_b32_e32 v114, 16, v38
	v_and_b32_e32 v115, 0xffff0000, v38
	v_lshlrev_b32_e32 v116, 16, v42
	v_and_b32_e32 v117, 0xffff0000, v42
	v_lshlrev_b32_e32 v118, 16, v39
	v_and_b32_e32 v119, 0xffff0000, v39
	v_lshlrev_b32_e32 v120, 16, v43
	v_and_b32_e32 v121, 0xffff0000, v43
	s_waitcnt vmcnt(0)
	v_mov_b64_e32 v[36:37], v[88:89]
	v_mov_b64_e32 v[40:41], v[80:81]
	v_lshlrev_b32_e32 v124, 16, v72
	v_and_b32_e32 v125, 0xffff0000, v72
	v_lshlrev_b32_e32 v72, 16, v73
	v_and_b32_e32 v73, 0xffff0000, v73
	v_lshlrev_b32_e32 v130, 16, v74
	v_and_b32_e32 v131, 0xffff0000, v74
	v_lshlrev_b32_e32 v74, 16, v75
	v_and_b32_e32 v75, 0xffff0000, v75
	v_lshlrev_b32_e32 v134, 16, v80
	v_and_b32_e32 v135, 0xffff0000, v80
	v_lshlrev_b32_e32 v136, 16, v81
	v_and_b32_e32 v137, 0xffff0000, v81
	v_lshlrev_b32_e32 v142, 16, v82
	v_and_b32_e32 v143, 0xffff0000, v82
	v_lshlrev_b32_e32 v144, 16, v83
	v_and_b32_e32 v145, 0xffff0000, v83
	v_lshlrev_b32_e32 v148, 16, v88
	v_and_b32_e32 v149, 0xffff0000, v88
	v_lshlrev_b32_e32 v150, 16, v89
	v_and_b32_e32 v151, 0xffff0000, v89
	v_lshlrev_b32_e32 v154, 16, v90
	v_and_b32_e32 v155, 0xffff0000, v90
	v_lshlrev_b32_e32 v156, 16, v91
	v_and_b32_e32 v157, 0xffff0000, v91
	v_mov_b64_e32 v[38:39], v[90:91]
	v_mov_b64_e32 v[42:43], v[82:83]
	v_pk_fma_f32 v[58:59], v[32:33], v[108:109], v[58:59]
	v_pk_fma_f32 v[80:81], v[34:35], v[112:113], v[92:93]
	v_pk_fma_f32 v[82:83], v[28:29], v[116:117], v[94:95]
	v_pk_fma_f32 v[88:89], v[30:31], v[120:121], v[96:97]
	v_pk_mul_f32 v[90:91], v[24:25], v[108:109]
	v_pk_mul_f32 v[92:93], v[26:27], v[112:113]
	v_pk_mul_f32 v[94:95], v[20:21], v[116:117]
	v_pk_mul_f32 v[96:97], v[22:23], v[120:121]
	v_pk_mul_f32 v[160:161], v[24:25], v[124:125]
	v_pk_mul_f32 v[162:163], v[26:27], v[72:73]
	v_pk_mul_f32 v[164:165], v[20:21], v[130:131]
	v_pk_mul_f32 v[166:167], v[22:23], v[74:75]
	v_pk_mul_f32 v[168:169], v[24:25], v[134:135]
	v_pk_mul_f32 v[170:171], v[26:27], v[136:137]
	v_pk_mul_f32 v[172:173], v[20:21], v[142:143]
	v_pk_mul_f32 v[174:175], v[22:23], v[144:145]
	v_pk_mul_f32 v[58:59], v[58:59], v[106:107]
	v_pk_mul_f32 v[80:81], v[80:81], v[110:111]
	v_pk_mul_f32 v[82:83], v[82:83], v[114:115]
	v_pk_mul_f32 v[88:89], v[88:89], v[118:119]
	v_pk_fma_f32 v[90:91], v[16:17], v[50:51], v[90:91]
	v_pk_fma_f32 v[92:93], v[18:19], v[52:53], v[92:93]
	v_pk_fma_f32 v[54:55], v[12:13], v[54:55], v[94:95]
	v_pk_fma_f32 v[56:57], v[14:15], v[56:57], v[96:97]
	v_lshlrev_b32_e32 v122, 16, v68
	v_and_b32_e32 v123, 0xffff0000, v68
	v_lshlrev_b32_e32 v68, 16, v69
	v_and_b32_e32 v69, 0xffff0000, v69
	v_lshlrev_b32_e32 v126, 16, v70
	v_and_b32_e32 v127, 0xffff0000, v70
	v_lshlrev_b32_e32 v70, 16, v71
	v_and_b32_e32 v71, 0xffff0000, v71
	v_pk_fma_f32 v[94:95], v[16:17], v[108:109], v[160:161]
	v_pk_fma_f32 v[96:97], v[18:19], v[112:113], v[162:163]
	v_pk_fma_f32 v[106:107], v[12:13], v[116:117], v[164:165]
	v_pk_fma_f32 v[108:109], v[14:15], v[120:121], v[166:167]
	v_pk_fma_f32 v[110:111], v[16:17], v[124:125], v[168:169]
	v_pk_fma_f32 v[112:113], v[18:19], v[72:73], v[170:171]
	v_pk_fma_f32 v[114:115], v[12:13], v[130:131], v[172:173]
	v_pk_fma_f32 v[116:117], v[14:15], v[74:75], v[174:175]
	v_cvt_pk_bf16_f32 v50, v58, v59
	v_cvt_pk_bf16_f32 v51, v80, v81
	v_cvt_pk_bf16_f32 v52, v82, v83
	v_cvt_pk_bf16_f32 v53, v88, v89
	v_pk_fma_f32 v[58:59], v[32:33], v[124:125], v[90:91]
	v_pk_fma_f32 v[72:73], v[34:35], v[72:73], v[92:93]
	v_pk_fma_f32 v[54:55], v[28:29], v[130:131], v[54:55]
	v_pk_fma_f32 v[56:57], v[30:31], v[74:75], v[56:57]
	v_lshlrev_b32_e32 v132, 16, v76
	v_and_b32_e32 v133, 0xffff0000, v76
	v_lshlrev_b32_e32 v76, 16, v77
	v_and_b32_e32 v77, 0xffff0000, v77
	v_lshlrev_b32_e32 v138, 16, v78
	v_and_b32_e32 v139, 0xffff0000, v78
	v_lshlrev_b32_e32 v78, 16, v79
	v_and_b32_e32 v79, 0xffff0000, v79
	v_lshlrev_b32_e32 v146, 16, v84
	v_and_b32_e32 v147, 0xffff0000, v84
	v_lshlrev_b32_e32 v84, 16, v85
	v_and_b32_e32 v85, 0xffff0000, v85
	v_lshlrev_b32_e32 v152, 16, v86
	v_and_b32_e32 v153, 0xffff0000, v86
	v_lshlrev_b32_e32 v86, 16, v87
	v_and_b32_e32 v87, 0xffff0000, v87
	v_pk_fma_f32 v[74:75], v[32:33], v[134:135], v[94:95]
	v_pk_fma_f32 v[80:81], v[34:35], v[136:137], v[96:97]
	v_pk_fma_f32 v[82:83], v[28:29], v[142:143], v[106:107]
	v_pk_fma_f32 v[88:89], v[30:31], v[144:145], v[108:109]
	v_pk_fma_f32 v[90:91], v[32:33], v[148:149], v[110:111]
	v_pk_fma_f32 v[92:93], v[34:35], v[150:151], v[112:113]
	v_pk_fma_f32 v[94:95], v[28:29], v[154:155], v[114:115]
	v_pk_fma_f32 v[96:97], v[30:31], v[156:157], v[116:117]
	global_store_dwordx4 v[98:99], v[50:53], off offset:1024
	v_pk_mul_f32 v[54:55], v[54:55], v[126:127]
	v_pk_mul_f32 v[56:57], v[56:57], v[70:71]
	v_pk_mul_f32 v[50:51], v[58:59], v[122:123]
	v_pk_mul_f32 v[52:53], v[72:73], v[68:69]
	v_pk_mul_f32 v[58:59], v[74:75], v[132:133]
	v_pk_mul_f32 v[68:69], v[80:81], v[76:77]
	v_pk_mul_f32 v[70:71], v[82:83], v[138:139]
	v_pk_mul_f32 v[72:73], v[88:89], v[78:79]
	v_pk_mul_f32 v[74:75], v[90:91], v[146:147]
	v_pk_mul_f32 v[76:77], v[92:93], v[84:85]
	v_pk_mul_f32 v[78:79], v[94:95], v[152:153]
	v_pk_mul_f32 v[80:81], v[96:97], v[86:87]
	v_cvt_pk_bf16_f32 v50, v50, v51
	v_cvt_pk_bf16_f32 v51, v52, v53
	v_cvt_pk_bf16_f32 v52, v54, v55
	v_cvt_pk_bf16_f32 v53, v56, v57
	v_cvt_pk_bf16_f32 v54, v58, v59
	v_cvt_pk_bf16_f32 v55, v68, v69
	v_cvt_pk_bf16_f32 v56, v70, v71
	v_cvt_pk_bf16_f32 v57, v72, v73
	v_cvt_pk_bf16_f32 v68, v74, v75
	v_cvt_pk_bf16_f32 v69, v76, v77
	v_cvt_pk_bf16_f32 v70, v78, v79
	v_cvt_pk_bf16_f32 v71, v80, v81
	global_store_dwordx4 v[100:101], v[50:53], off offset:1024
	global_store_dwordx4 v[102:103], v[54:57], off offset:1024
	global_store_dwordx4 v[104:105], v[68:71], off offset:1024
	s_cbranch_scc0 .Lcq_438
	s_movk_i32 s22, 0x200
	s_mov_b64 s[18:19], 0
	s_and_b64 vcc, exec, s[16:17]
	s_cbranch_vccz .Lcq_434
	v_mov_b32_e32 v164, v200
	v_mbcnt_hi_u32_b32 v155, -1, v194
	v_and_b32_e32 v0, 64, v155
	v_mov_b32_e32 v154, 0x358637bd
	v_xor_b32_e32 v156, 32, v155
	v_add_u32_e32 v157, 64, v0
	v_mov_b32_e32 v158, 0xf149f2ca
	v_mov_b32_e32 v159, 0x7149f2ca
	v_mov_b32_e32 v160, 0x2080
	v_mov_b32_e32 v161, 0x461c4000
	v_mov_b32_e32 v162, 0xffffff80
	v_mov_b32_e32 v163, 0x63
	s_branch .Lp3_item_end
